# P6 chunk-out: K/n0/C0/V-gather loads hoisted and batched per block (distinct dest regs, counted vmcnt) + attention max3/permlane cleanup + QK split + P3 rewrite
# speedup vs baseline: 1.0390x; 1.0200x over previous
.LBB0_688:
	s_add_i32 s73, s95, 0
	v_add3_u32 v1, s73, v241, v224
	ds_read_b128 v[2:5], v1
	ds_read_b128 v[6:9], v1 offset:6656
	ds_read_b128 v[10:13], v1 offset:32
	s_waitcnt lgkmcnt(2)
	v_mfma_f32_32x32x16_bf16 v[148:163], v[2:5], v[176:179], 0
	ds_read_b128 v[2:5], v1 offset:6688
	s_waitcnt lgkmcnt(2)
	v_mfma_f32_32x32x16_bf16 v[80:95], v[6:9], v[176:179], 0
	ds_read_b128 v[6:9], v1 offset:64
	s_waitcnt lgkmcnt(2)
	v_mfma_f32_32x32x16_bf16 v[148:163], v[10:13], v[180:183], v[148:163]
	ds_read_b128 v[10:13], v1 offset:6720
	s_waitcnt lgkmcnt(2)
	v_mfma_f32_32x32x16_bf16 v[80:95], v[2:5], v[180:183], v[80:95]
	ds_read_b128 v[2:5], v1 offset:96
	s_waitcnt lgkmcnt(2)
	v_mfma_f32_32x32x16_bf16 v[148:163], v[6:9], v[184:187], v[148:163]
	ds_read_b128 v[6:9], v1 offset:6752
	s_waitcnt lgkmcnt(2)
	v_mfma_f32_32x32x16_bf16 v[80:95], v[10:13], v[184:187], v[80:95]
	ds_read_b128 v[10:13], v1 offset:128
	s_waitcnt lgkmcnt(2)
	v_mfma_f32_32x32x16_bf16 v[148:163], v[2:5], v[188:191], v[148:163]
	ds_read_b128 v[2:5], v1 offset:6784
	s_waitcnt lgkmcnt(2)
	v_mfma_f32_32x32x16_bf16 v[80:95], v[6:9], v[188:191], v[80:95]
	ds_read_b128 v[6:9], v1 offset:160
	s_waitcnt lgkmcnt(2)
	v_mfma_f32_32x32x16_bf16 v[148:163], v[10:13], v[192:195], v[148:163]
	ds_read_b128 v[10:13], v1 offset:6816
	s_waitcnt lgkmcnt(2)
	v_mfma_f32_32x32x16_bf16 v[80:95], v[2:5], v[192:195], v[80:95]
	s_waitcnt lgkmcnt(1)
	v_mfma_f32_32x32x16_bf16 v[148:163], v[6:9], v[196:199], v[148:163]
	s_waitcnt lgkmcnt(0)
	v_mfma_f32_32x32x16_bf16 v[80:95], v[10:13], v[196:199], v[80:95]
	s_cmp_eq_u32 s74, s90
	s_cselect_b64 s[86:87], -1, 0
	s_cmp_lg_u32 s74, s90
	s_nop 9
	v_sub_f32_e32 v99, v163, v244
	v_sub_f32_e32 v100, v162, v244
	v_sub_f32_e32 v101, v161, v244
	v_sub_f32_e32 v102, v160, v244
	v_sub_f32_e32 v103, v159, v244
	v_sub_f32_e32 v104, v158, v244
	v_sub_f32_e32 v105, v157, v244
	v_sub_f32_e32 v106, v156, v244
	v_sub_f32_e32 v107, v155, v244
	v_sub_f32_e32 v108, v154, v244
	v_sub_f32_e32 v109, v153, v244
	v_sub_f32_e32 v110, v152, v244
	v_sub_f32_e32 v111, v151, v244
	v_sub_f32_e32 v112, v150, v244
	v_sub_f32_e32 v113, v149, v244
	v_sub_f32_e32 v114, v148, v244
	s_cbranch_scc1 .LBB0_690
	v_cndmask_b32_e64 v1, v114, v0, s[8:9]
	v_mov_b32_e32 v14, v0
	v_mov_b32_e32 v15, v0
	v_cndmask_b32_e64 v114, v1, v114, s[10:11]
	v_mov_b32_e32 v1, v0
	v_mov_b32_e32 v2, v0
	v_mov_b32_e32 v3, v0
	v_mov_b32_e32 v4, v0
	v_mov_b32_e32 v5, v0
	v_mov_b32_e32 v6, v0
	v_mov_b32_e32 v7, v0
	v_mov_b32_e32 v8, v0
	v_mov_b32_e32 v9, v0
	v_mov_b32_e32 v10, v0
	v_mov_b32_e32 v11, v0
	v_mov_b32_e32 v12, v0
	v_mov_b32_e32 v13, v0
	v_mov_b64_e32 v[94:95], v[14:15]
	v_cndmask_b32_e64 v113, v0, v113, s[10:11]
	v_cndmask_b32_e64 v112, v112, v0, s[12:13]
	v_cndmask_b32_e64 v111, v111, v0, s[14:15]
	v_cndmask_b32_e64 v110, v110, v0, s[16:17]
	v_cndmask_b32_e64 v109, v109, v0, s[18:19]
	v_cndmask_b32_e64 v108, v108, v0, s[20:21]
	v_cndmask_b32_e64 v107, v107, v0, s[22:23]
	v_cndmask_b32_e64 v106, v106, v0, s[24:25]
	v_cndmask_b32_e64 v105, v105, v0, s[26:27]
	v_cndmask_b32_e64 v104, v104, v0, s[28:29]
	v_cndmask_b32_e64 v103, v103, v0, s[30:31]
	v_cndmask_b32_e64 v102, v102, v0, s[34:35]
	v_cndmask_b32_e64 v101, v101, v0, s[36:37]
	v_cndmask_b32_e64 v100, v100, v0, s[38:39]
	v_cndmask_b32_e64 v99, v99, v0, s[40:41]
	v_mov_b64_e32 v[92:93], v[12:13]
	v_mov_b64_e32 v[90:91], v[10:11]
	v_mov_b64_e32 v[88:89], v[8:9]
	v_mov_b64_e32 v[86:87], v[6:7]
	v_mov_b64_e32 v[84:85], v[4:5]
	v_mov_b64_e32 v[82:83], v[2:3]
	v_mov_b64_e32 v[80:81], v[0:1]
	s_branch .LBB0_691

.LBB0_691:
	v_max3_f32 v1, v99, v101, v103
	v_max3_f32 v2, v100, v102, v104
	v_max3_f32 v1, v1, v105, v107
	v_max3_f32 v2, v2, v106, v108
	v_max3_f32 v1, v1, v109, v111
	v_max3_f32 v2, v2, v110, v112
	v_max3_f32 v1, v1, v113, v80
	v_max3_f32 v2, v2, v114, v81
	v_max3_f32 v1, v1, v82, v84
	v_max3_f32 v2, v2, v83, v85
	v_max3_f32 v1, v1, v86, v88
	v_max3_f32 v2, v2, v87, v89
	v_max3_f32 v1, v1, v90, v92
	v_max3_f32 v2, v2, v91, v93
	v_max_f32_e32 v1, v1, v94
	v_max_f32_e32 v2, v2, v95
	v_max_f32_e32 v1, v1, v2
	s_cmp_lg_u32 s90, 0
	s_cselect_b64 s[88:89], -1, 0
	v_mov_b32_e32 v2, v1
	s_cmp_eq_u32 s90, 0
	s_nop 0
	v_permlane32_swap_b32_e32 v1, v2
	v_max_f32_e32 v1, v1, v2
	s_cbranch_scc1 .LBB0_694
	v_cmp_lt_f32_e32 vcc, s72, v1
	s_cbranch_vccz .LBB0_709
	v_max_f32_e32 v1, v1, v1
	v_max_f32_e32 v1, 0, v1

.LBB0_696:
	v_add3_u32 v1, s73, v241, v224
	ds_read_b128 v[2:5], v1 offset:6656
	ds_read_b128 v[6:9], v1
	ds_read_b128 v[10:13], v1 offset:6688
	s_waitcnt lgkmcnt(2)
	v_mfma_f32_32x32x16_bf16 v[132:147], v[2:5], v[200:203], 0
	ds_read_b128 v[2:5], v1 offset:32
	s_waitcnt lgkmcnt(2)
	v_mfma_f32_32x32x16_bf16 v[116:131], v[6:9], v[200:203], 0
	ds_read_b128 v[6:9], v1 offset:6720
	s_waitcnt lgkmcnt(2)
	v_mfma_f32_32x32x16_bf16 v[132:147], v[10:13], v[204:207], v[132:147]
	ds_read_b128 v[10:13], v1 offset:64
	s_waitcnt lgkmcnt(2)
	v_mfma_f32_32x32x16_bf16 v[116:131], v[2:5], v[204:207], v[116:131]
	ds_read_b128 v[2:5], v1 offset:6752
	s_waitcnt lgkmcnt(2)
	v_mfma_f32_32x32x16_bf16 v[132:147], v[6:9], v[208:211], v[132:147]
	ds_read_b128 v[6:9], v1 offset:96
	s_waitcnt lgkmcnt(2)
	v_mfma_f32_32x32x16_bf16 v[116:131], v[10:13], v[208:211], v[116:131]
	ds_read_b128 v[10:13], v1 offset:6784
	s_waitcnt lgkmcnt(2)
	v_mfma_f32_32x32x16_bf16 v[132:147], v[2:5], v[212:215], v[132:147]
	ds_read_b128 v[2:5], v1 offset:128
	s_waitcnt lgkmcnt(2)
	v_mfma_f32_32x32x16_bf16 v[116:131], v[6:9], v[212:215], v[116:131]
	ds_read_b128 v[6:9], v1 offset:6816
	s_waitcnt lgkmcnt(2)
	v_mfma_f32_32x32x16_bf16 v[132:147], v[10:13], v[216:219], v[132:147]
	ds_read_b128 v[10:13], v1 offset:160
	s_waitcnt lgkmcnt(2)
	v_mfma_f32_32x32x16_bf16 v[116:131], v[2:5], v[216:219], v[116:131]
	s_waitcnt lgkmcnt(1)
	v_mfma_f32_32x32x16_bf16 v[132:147], v[6:9], v[220:223], v[132:147]
	s_waitcnt lgkmcnt(0)
	v_mfma_f32_32x32x16_bf16 v[116:131], v[10:13], v[220:223], v[116:131]
	s_nop 10
	v_sub_f32_e32 v15, v147, v245
	v_sub_f32_e32 v14, v146, v245
	v_sub_f32_e32 v13, v145, v245
	v_sub_f32_e32 v12, v144, v245
	v_sub_f32_e32 v11, v143, v245
	v_sub_f32_e32 v10, v142, v245
	v_sub_f32_e32 v9, v141, v245
	v_sub_f32_e32 v8, v140, v245
	v_sub_f32_e32 v7, v139, v245
	v_sub_f32_e32 v6, v138, v245
	v_sub_f32_e32 v5, v137, v245
	v_sub_f32_e32 v4, v136, v245
	v_sub_f32_e32 v3, v135, v245
	v_sub_f32_e32 v2, v134, v245
	s_andn2_b64 vcc, exec, s[86:87]
	v_sub_f32_e32 v1, v133, v245
	v_sub_f32_e32 v96, v132, v245
	s_cbranch_vccnz .LBB0_698
	v_cndmask_b32_e64 v96, v96, v0, s[8:9]
	v_cndmask_b32_e64 v1, v1, v0, s[42:43]
	v_cndmask_b32_e64 v2, v2, v0, s[44:45]
	v_cndmask_b32_e64 v3, v3, v0, s[46:47]
	v_cndmask_b32_e64 v4, v4, v0, s[48:49]
	v_cndmask_b32_e64 v5, v5, v0, s[50:51]
	v_cndmask_b32_e64 v6, v6, v0, s[52:53]
	v_cndmask_b32_e64 v7, v7, v0, s[54:55]
	v_cndmask_b32_e64 v8, v8, v0, s[56:57]
	v_cndmask_b32_e64 v9, v9, v0, s[58:59]
	v_cndmask_b32_e64 v10, v10, v0, s[60:61]
	v_cndmask_b32_e64 v11, v11, v0, s[62:63]
	v_cndmask_b32_e64 v12, v12, v0, s[64:65]
	v_cndmask_b32_e64 v13, v13, v0, s[66:67]
	v_cndmask_b32_e64 v14, v14, v0, s[68:69]
	v_cndmask_b32_e64 v15, v15, v0, s[70:71]
.LBB0_698:
	v_sub_f32_e32 v133, v117, v245
	v_sub_f32_e32 v136, v116, v245
	v_sub_f32_e32 v132, v118, v245
	v_sub_f32_e32 v135, v119, v245
	v_sub_f32_e32 v134, v120, v245
	v_sub_f32_e32 v121, v121, v245
	v_sub_f32_e32 v122, v122, v245
	v_sub_f32_e32 v123, v123, v245
	v_sub_f32_e32 v116, v124, v245
	v_sub_f32_e32 v115, v125, v245
	v_sub_f32_e32 v118, v126, v245
	v_sub_f32_e32 v117, v127, v245
	v_sub_f32_e32 v120, v128, v245
	v_sub_f32_e32 v119, v129, v245
	v_sub_f32_e32 v97, v131, v245
	v_sub_f32_e32 v98, v130, v245
	v_max3_f32 v124, v136, v132, v134
	v_max3_f32 v125, v133, v135, v121
	v_max3_f32 v124, v124, v122, v116
	v_max3_f32 v125, v125, v123, v115
	v_max3_f32 v124, v124, v118, v120
	v_max3_f32 v125, v125, v117, v119
	v_max3_f32 v124, v124, v98, v96
	v_max3_f32 v125, v125, v97, v1
	v_max3_f32 v124, v124, v2, v4
	v_max3_f32 v125, v125, v3, v5
	v_max3_f32 v124, v124, v6, v8
	v_max3_f32 v125, v125, v7, v9
	v_max3_f32 v124, v124, v10, v12
	v_max3_f32 v125, v125, v11, v13
	v_max_f32_e32 v124, v124, v14
	v_max_f32_e32 v125, v125, v15
	v_max_f32_e32 v124, v124, v125
	s_andn2_b64 vcc, exec, s[88:89]
	v_mov_b32_e32 v125, v124
	s_nop 1
	v_permlane32_swap_b32_e32 v124, v125
	v_max_f32_e32 v124, v124, v125
	s_cbranch_vccnz .LBB0_701
	v_cmp_lt_f32_e32 vcc, s72, v124
	s_cbranch_vccz .LBB0_710
	v_max_f32_e32 v124, v124, v124
	v_max_f32_e32 v124, 0, v124

.LBB0_853:
	s_and_b64 vcc, exec, s[4:5]
	v_and_b32_e32 v180, 31, v180
	v_or_b32_e32 v101, s2, v180
	v_or_b32_e32 v0, v101, v171
	v_and_b32_e32 v181, 1, v181
	v_lshlrev_b32_e32 v0, 2, v0
	v_lshlrev_b32_e32 v92, 7, v101
	ds_bpermute_b32 v71, v0, v182
	ds_bpermute_b32 v73, v0, v184
	v_lshl_add_u64 v[0:1], s[0:1], 0, v[92:93]
	v_lshlrev_b32_e32 v92, 4, v181
	v_lshl_add_u64 v[0:1], v[0:1], 0, v[92:93]
	global_load_dwordx4 v[44:47], v[0:1], off
	global_load_dwordx4 v[40:43], v[0:1], off offset:32
	global_load_dwordx4 v[36:39], v[0:1], off offset:64
	global_load_dwordx4 v[32:35], v[0:1], off offset:96
	v_lshl_add_u64 v[0:1], s[6:7], 0, v[92:93]
	v_lshlrev_b32_e32 v92, 7, v180
	v_lshl_add_u64 v[50:51], v[0:1], 0, v[92:93]
	global_load_dwordx4 v[196:199], v[50:51], off
	global_load_dwordx4 v[200:203], v[50:51], off offset:32
	global_load_dwordx4 v[204:207], v[50:51], off offset:64
	global_load_dwordx4 v[208:211], v[50:51], off offset:96
	v_mov_b32_e32 v250, 0x1000
	v_mov_b32_e32 v251, 0
	v_lshlrev_b32_e32 v140, 5, v181
	v_lshl_add_u64 v[252:253], v[50:51], 0, v[250:251]
	global_load_dwordx4 v[212:215], v[252:253], off
	global_load_dwordx4 v[216:219], v[252:253], off offset:32
	global_load_dwordx4 v[220:223], v[252:253], off offset:64
	global_load_dwordx4 v[224:227], v[252:253], off offset:96
	global_load_dwordx4 v[108:111], v140, s[10:11]
	global_load_dwordx4 v[112:115], v140, s[10:11] offset:16
	global_load_dwordx4 v[116:119], v140, s[10:11] offset:64
	global_load_dwordx4 v[120:123], v140, s[10:11] offset:80
	global_load_dwordx4 v[124:127], v140, s[10:11] offset:128
	global_load_dwordx4 v[128:131], v140, s[10:11] offset:144
	global_load_dwordx4 v[132:135], v140, s[10:11] offset:192
	global_load_dwordx4 v[136:139], v140, s[10:11] offset:208
	v_lshlrev_b32_e32 v96, 2, v181
	v_or_b32_e32 v104, 1, v96
	v_or_b32_e32 v100, 2, v96
	v_or_b32_e32 v97, 3, v96
	v_or_b32_e32 v62, 8, v96
	v_or_b32_e32 v63, 9, v96
	v_or_b32_e32 v60, 10, v96
	v_or_b32_e32 v61, 11, v96
	v_or_b32_e32 v58, 16, v96
	v_or_b32_e32 v59, 17, v96
	v_or_b32_e32 v56, 18, v96
	v_or_b32_e32 v57, 19, v96
	v_or_b32_e32 v54, 24, v96
	v_or_b32_e32 v55, 25, v96
	v_or_b32_e32 v52, 26, v96
	v_or_b32_e32 v53, 27, v96
	v_mov_b32_e32 v49, v96
	v_mov_b32_e32 v4, 0
	v_mov_b32_e32 v5, 0
	v_mov_b32_e32 v6, 0
	v_mov_b32_e32 v7, 0
	v_mov_b32_e32 v8, 0
	v_mov_b32_e32 v9, 0
	v_mov_b32_e32 v10, 0
	v_mov_b32_e32 v11, 0
	v_mov_b32_e32 v12, 0
	v_mov_b32_e32 v13, 0
	v_mov_b32_e32 v14, 0
	v_mov_b32_e32 v15, 0
	s_waitcnt vmcnt(15)
	v_mfma_f32_32x32x16_bf16 v[16:31], v[196:199], v[44:47], 0
	s_waitcnt vmcnt(14)
	v_mfma_f32_32x32x16_bf16 v[16:31], v[200:203], v[40:43], v[16:31]
	s_waitcnt vmcnt(13)
	v_mfma_f32_32x32x16_bf16 v[16:31], v[204:207], v[36:39], v[16:31]
	s_waitcnt vmcnt(12)
	v_mfma_f32_32x32x16_bf16 v[16:31], v[208:211], v[32:35], v[16:31]
	v_or_b32_e32 v0, v96, v171
	v_lshlrev_b32_e32 v0, 2, v0
	ds_bpermute_b32 v80, v0, v183
	v_or_b32_e32 v0, v104, v171
	v_lshlrev_b32_e32 v0, 2, v0
	ds_bpermute_b32 v79, v0, v183
	v_or_b32_e32 v0, v100, v171
	v_lshlrev_b32_e32 v0, 2, v0
	ds_bpermute_b32 v78, v0, v183
	v_or_b32_e32 v0, v97, v171
	v_lshlrev_b32_e32 v0, 2, v0
	ds_bpermute_b32 v77, v0, v183
	v_or_b32_e32 v0, v62, v171
	v_lshlrev_b32_e32 v0, 2, v0
	ds_bpermute_b32 v76, v0, v183
	v_or_b32_e32 v0, v63, v171
	v_lshlrev_b32_e32 v0, 2, v0
	ds_bpermute_b32 v75, v0, v183
	v_or_b32_e32 v0, v60, v171
	v_lshlrev_b32_e32 v0, 2, v0
	ds_bpermute_b32 v74, v0, v183
	v_or_b32_e32 v0, v61, v171
	v_lshlrev_b32_e32 v0, 2, v0
	ds_bpermute_b32 v72, v0, v183
	v_or_b32_e32 v0, v58, v171
	v_lshlrev_b32_e32 v0, 2, v0
	ds_bpermute_b32 v70, v0, v183
	v_or_b32_e32 v0, v59, v171
	v_lshlrev_b32_e32 v0, 2, v0
	ds_bpermute_b32 v69, v0, v183
	v_or_b32_e32 v0, v56, v171
	v_lshlrev_b32_e32 v0, 2, v0
	ds_bpermute_b32 v68, v0, v183
	v_or_b32_e32 v0, v57, v171
	v_lshlrev_b32_e32 v0, 2, v0
	ds_bpermute_b32 v67, v0, v183
	v_or_b32_e32 v0, v54, v171
	v_lshlrev_b32_e32 v0, 2, v0
	ds_bpermute_b32 v66, v0, v183
	v_or_b32_e32 v0, v55, v171
	v_lshlrev_b32_e32 v0, 2, v0
	ds_bpermute_b32 v65, v0, v183
	v_or_b32_e32 v0, v52, v171
	v_lshlrev_b32_e32 v0, 2, v0
	ds_bpermute_b32 v64, v0, v183
	v_or_b32_e32 v0, v53, v171
	v_lshlrev_b32_e32 v0, 2, v0
	ds_bpermute_b32 v48, v0, v183
	v_mov_b32_e32 v0, 0
	v_mov_b32_e32 v1, 0
	v_mov_b32_e32 v2, 0
	v_mov_b32_e32 v3, 0
	s_cbranch_vccnz .LBB0_855
	s_waitcnt vmcnt(11)
	v_mfma_f32_32x32x16_bf16 v[0:15], v[212:215], v[44:47], 0
	s_waitcnt vmcnt(10)
	v_mfma_f32_32x32x16_bf16 v[0:15], v[216:219], v[40:43], v[0:15]
	s_waitcnt vmcnt(9)
	v_mfma_f32_32x32x16_bf16 v[0:15], v[220:223], v[36:39], v[0:15]
	s_waitcnt vmcnt(8)
	v_mfma_f32_32x32x16_bf16 v[0:15], v[224:227], v[32:35], v[0:15]
.LBB0_855:
	s_waitcnt lgkmcnt(14)
	v_max_f32_e32 v50, v73, v73
	v_max_f32_e32 v51, v185, v185
	v_max_f32_e32 v50, v51, v50
	v_add_f32_e32 v99, v50, v71
	v_add_f32_e32 v50, v185, v71
	v_sub_f32_e32 v50, v50, v99
	v_mul_f32_e32 v50, 0x3fb8aa3b, v50
	v_exp_f32_e32 v98, v50
	v_sub_f32_e32 v50, v71, v99
	v_add_f32_e32 v71, v50, v79
	v_mul_f32_e32 v71, 0x3fb8aa3b, v71
	v_exp_f32_e32 v71, v71
	v_add_f32_e32 v51, v50, v80
	v_mul_f32_e32 v51, 0x3fb8aa3b, v51
	v_cmp_gt_u32_e32 vcc, v101, v96
	s_waitcnt lgkmcnt(12)
	v_add_f32_e32 v73, v50, v77
	v_exp_f32_e32 v51, v51
	v_cndmask_b32_e32 v81, 0, v71, vcc
	v_add_f32_e32 v71, v50, v78
	v_mul_f32_e32 v73, 0x3fb8aa3b, v73
	v_mul_f32_e32 v71, 0x3fb8aa3b, v71
	v_exp_f32_e32 v73, v73
	v_exp_f32_e32 v71, v71
	v_cmp_le_u32_e32 vcc, v96, v101
	s_waitcnt lgkmcnt(8)
	v_add_f32_e32 v72, v50, v72
	v_mul_f32_e32 v72, 0x3fb8aa3b, v72
	v_cndmask_b32_e32 v80, 0, v51, vcc
	v_cmp_le_u32_e32 vcc, v97, v101
	v_exp_f32_e32 v72, v72
	s_waitcnt lgkmcnt(6)
	v_add_f32_e32 v69, v50, v69
	v_cndmask_b32_e32 v79, 0, v73, vcc
	v_cmp_le_u32_e32 vcc, v100, v101
	v_add_f32_e32 v73, v50, v75
	v_mul_f32_e32 v73, 0x3fb8aa3b, v73
	v_cndmask_b32_e32 v78, 0, v71, vcc
	v_add_f32_e32 v71, v50, v76
	v_mul_f32_e32 v71, 0x3fb8aa3b, v71
	v_exp_f32_e32 v73, v73
	v_exp_f32_e32 v71, v71
	v_cmp_le_u32_e32 vcc, v63, v101
	v_add_f32_e32 v70, v50, v70
	v_mul_f32_e32 v69, 0x3fb8aa3b, v69
	v_cndmask_b32_e32 v77, 0, v73, vcc
	v_cmp_le_u32_e32 vcc, v62, v101
	v_mul_f32_e32 v70, 0x3fb8aa3b, v70
	v_exp_f32_e32 v69, v69
	v_cndmask_b32_e32 v76, 0, v71, vcc
	v_add_f32_e32 v71, v50, v74
	v_mul_f32_e32 v71, 0x3fb8aa3b, v71
	v_exp_f32_e32 v71, v71
	s_waitcnt lgkmcnt(4)
	v_add_f32_e32 v67, v50, v67
	v_cmp_le_u32_e32 vcc, v61, v101
	v_exp_f32_e32 v70, v70
	v_add_f32_e32 v68, v50, v68
	v_mul_f32_e32 v67, 0x3fb8aa3b, v67
	v_cndmask_b32_e32 v73, 0, v72, vcc
	v_cmp_le_u32_e32 vcc, v60, v101
	v_mul_f32_e32 v68, 0x3fb8aa3b, v68
	v_exp_f32_e32 v67, v67
	v_cndmask_b32_e32 v72, 0, v71, vcc
	v_cmp_le_u32_e32 vcc, v59, v101
	v_exp_f32_e32 v68, v68
	v_pk_mul_f32 v[16:17], v[16:17], v[80:81]
	v_cndmask_b32_e32 v71, 0, v69, vcc
	v_cmp_le_u32_e32 vcc, v58, v101
	v_add_f32_e32 v51, 0, v16
	v_add_f32_e32 v51, v51, v17
	v_cndmask_b32_e32 v70, 0, v70, vcc
	v_cmp_le_u32_e32 vcc, v57, v101
	v_pk_mul_f32 v[18:19], v[18:19], v[78:79]
	s_waitcnt lgkmcnt(2)
	v_add_f32_e32 v65, v50, v65
	v_cndmask_b32_e32 v69, 0, v67, vcc
	v_cmp_le_u32_e32 vcc, v56, v101
	v_add_f32_e32 v51, v51, v18
	v_add_f32_e32 v51, v51, v19
	v_cndmask_b32_e32 v68, 0, v68, vcc
	v_pk_mul_f32 v[26:27], v[26:27], v[68:69]
	v_cvt_pk_bf16_f32 v68, v16, v17
	v_or_b32_e32 v17, 33, v49
	v_cvt_pk_bf16_f32 v69, v18, v19
	v_or_b32_e32 v16, 32, v96
	v_or_b32_e32 v19, v17, v171
	v_or_b32_e32 v18, v16, v171
	v_lshlrev_b32_e32 v19, 2, v19
	v_lshlrev_b32_e32 v18, 2, v18
	ds_bpermute_b32 v19, v19, v183
	ds_bpermute_b32 v18, v18, v183
	v_add_f32_e32 v66, v50, v66
	v_mul_f32_e32 v65, 0x3fb8aa3b, v65
	v_mul_f32_e32 v66, 0x3fb8aa3b, v66
	v_exp_f32_e32 v65, v65
	s_waitcnt lgkmcnt(2)
	v_add_f32_e32 v48, v50, v48
	v_exp_f32_e32 v66, v66
	v_add_f32_e32 v64, v50, v64
	v_mul_f32_e32 v48, 0x3fb8aa3b, v48
	v_mul_f32_e32 v64, 0x3fb8aa3b, v64
	v_exp_f32_e32 v48, v48
	s_waitcnt lgkmcnt(1)
	v_add_f32_e32 v19, v50, v19
	v_cmp_le_u32_e32 vcc, v55, v101
	v_exp_f32_e32 v64, v64
	s_waitcnt lgkmcnt(0)
	v_add_f32_e32 v18, v50, v18
	v_mul_f32_e32 v19, 0x3fb8aa3b, v19
	v_cndmask_b32_e32 v67, 0, v65, vcc
	v_cmp_le_u32_e32 vcc, v54, v101
	v_mul_f32_e32 v18, 0x3fb8aa3b, v18
	v_exp_f32_e32 v19, v19
	v_cndmask_b32_e32 v66, 0, v66, vcc
	v_cmp_le_u32_e32 vcc, v53, v101
	v_exp_f32_e32 v18, v18
	v_pk_mul_f32 v[20:21], v[20:21], v[76:77]
	v_cndmask_b32_e32 v65, 0, v48, vcc
	v_cmp_le_u32_e32 vcc, v52, v101
	v_add_f32_e32 v51, v51, v20
	v_pk_mul_f32 v[24:25], v[24:25], v[70:71]
	v_cndmask_b32_e32 v64, 0, v64, vcc
	v_cmp_le_u32_e32 vcc, v17, v101
	v_cvt_pk_bf16_f32 v70, v20, v21
	v_or_b32_e32 v20, 34, v96
	v_cndmask_b32_e32 v19, 0, v19, vcc
	v_cmp_le_u32_e32 vcc, v16, v101
	v_add_f32_e32 v51, v51, v21
	v_pk_mul_f32 v[22:23], v[22:23], v[72:73]
	v_cndmask_b32_e32 v18, 0, v18, vcc
	v_pk_mul_f32 v[0:1], v[0:1], v[18:19]
	v_or_b32_e32 v19, v20, v171
	v_lshlrev_b32_e32 v19, 2, v19
	ds_bpermute_b32 v19, v19, v183
	v_or_b32_e32 v18, 35, v49
	v_cmp_le_u32_e32 vcc, v18, v101
	v_add_f32_e32 v51, v51, v22
	v_add_f32_e32 v51, v51, v23
	s_waitcnt lgkmcnt(0)
	v_add_f32_e32 v19, v50, v19
	v_mul_f32_e32 v19, 0x3fb8aa3b, v19
	v_exp_f32_e32 v21, v19
	v_or_b32_e32 v19, v18, v171
	v_lshlrev_b32_e32 v19, 2, v19
	ds_bpermute_b32 v19, v19, v183
	v_add_f32_e32 v51, v51, v24
	v_add_f32_e32 v51, v51, v25
	v_add_f32_e32 v51, v51, v26
	v_add_f32_e32 v51, v51, v27
	s_waitcnt lgkmcnt(0)
	v_add_f32_e32 v19, v50, v19
	v_mul_f32_e32 v19, 0x3fb8aa3b, v19
	v_exp_f32_e32 v19, v19
	v_pk_mul_f32 v[28:29], v[28:29], v[66:67]
	v_pk_mul_f32 v[30:31], v[30:31], v[64:65]
	v_add_f32_e32 v51, v51, v28
	v_cndmask_b32_e32 v19, 0, v19, vcc
	v_cmp_le_u32_e32 vcc, v20, v101
	v_or_b32_e32 v20, 40, v96
	v_add_f32_e32 v51, v51, v29
	v_cndmask_b32_e32 v18, 0, v21, vcc
	v_pk_mul_f32 v[2:3], v[2:3], v[18:19]
	v_or_b32_e32 v19, v20, v171
	v_lshlrev_b32_e32 v19, 2, v19
	ds_bpermute_b32 v19, v19, v183
	v_or_b32_e32 v18, 41, v49
	v_cmp_le_u32_e32 vcc, v18, v101
	v_add_f32_e32 v48, v51, v30
	v_add_f32_e32 v48, v48, v31
	s_waitcnt lgkmcnt(0)
	v_add_f32_e32 v19, v50, v19
	v_mul_f32_e32 v19, 0x3fb8aa3b, v19
	v_exp_f32_e32 v21, v19
	v_or_b32_e32 v19, v18, v171
	v_lshlrev_b32_e32 v19, 2, v19
	ds_bpermute_b32 v19, v19, v183
	v_add_f32_e32 v17, v48, v0
	v_add_f32_e32 v17, v17, v1
	v_add_f32_e32 v17, v17, v2
	v_add_f32_e32 v17, v17, v3
	s_waitcnt lgkmcnt(0)
	v_add_f32_e32 v19, v50, v19
	v_mul_f32_e32 v19, 0x3fb8aa3b, v19
	v_exp_f32_e32 v19, v19
	v_lshlrev_b32_e32 v92, 3, v181
	v_cvt_pk_bf16_f32 v76, v0, v1
	v_cvt_pk_bf16_f32 v77, v2, v3
	v_cndmask_b32_e32 v19, 0, v19, vcc
	v_cmp_le_u32_e32 vcc, v20, v101
	v_or_b32_e32 v20, 42, v96
	v_lshlrev_b32_e32 v102, 6, v180
	v_cndmask_b32_e32 v18, 0, v21, vcc
	v_pk_mul_f32 v[4:5], v[4:5], v[18:19]
	v_or_b32_e32 v19, v20, v171
	v_lshlrev_b32_e32 v19, 2, v19
	ds_bpermute_b32 v19, v19, v183
	v_or_b32_e32 v18, 43, v49
	v_cmp_le_u32_e32 vcc, v18, v101
	v_add_f32_e32 v17, v17, v4
	v_add_f32_e32 v17, v17, v5
	s_waitcnt lgkmcnt(0)
	v_add_f32_e32 v19, v50, v19
	v_mul_f32_e32 v19, 0x3fb8aa3b, v19
	v_exp_f32_e32 v21, v19
	v_or_b32_e32 v19, v18, v171
	v_lshlrev_b32_e32 v19, 2, v19
	ds_bpermute_b32 v19, v19, v183
	v_cvt_pk_bf16_f32 v78, v4, v5
	v_cvt_pk_bf16_f32 v64, v24, v25
	v_mul_u32_u24_e32 v24, 0x900, v61
	v_cvt_pk_bf16_f32 v71, v22, v23
	s_waitcnt lgkmcnt(0)
	v_add_f32_e32 v19, v50, v19
	v_mul_f32_e32 v19, 0x3fb8aa3b, v19
	v_exp_f32_e32 v19, v19
	v_cvt_pk_bf16_f32 v65, v26, v27
	v_cvt_pk_bf16_f32 v66, v28, v29
	v_cvt_pk_bf16_f32 v67, v30, v31
	v_cndmask_b32_e32 v19, 0, v19, vcc
	v_cmp_le_u32_e32 vcc, v20, v101
	v_or_b32_e32 v20, 48, v96
	s_xor_b64 s[24:25], s[4:5], -1
	v_cndmask_b32_e32 v18, 0, v21, vcc
	v_pk_mul_f32 v[6:7], v[6:7], v[18:19]
	v_or_b32_e32 v19, v20, v171
	v_lshlrev_b32_e32 v19, 2, v19
	ds_bpermute_b32 v19, v19, v183
	v_or_b32_e32 v18, 49, v49
	v_cmp_le_u32_e32 vcc, v18, v101
	v_add_f32_e32 v17, v17, v6
	v_add_f32_e32 v17, v17, v7
	s_waitcnt lgkmcnt(0)
	v_add_f32_e32 v19, v50, v19
	v_mul_f32_e32 v19, 0x3fb8aa3b, v19
	v_exp_f32_e32 v21, v19
	v_or_b32_e32 v19, v18, v171
	v_lshlrev_b32_e32 v19, 2, v19
	ds_bpermute_b32 v19, v19, v183
	v_cvt_pk_bf16_f32 v79, v6, v7
	v_mul_u32_u24_e32 v16, 0x900, v16
	v_lshlrev_b32_e32 v148, 1, v16
	s_waitcnt lgkmcnt(0)
	v_add_f32_e32 v19, v50, v19
	v_mul_f32_e32 v19, 0x3fb8aa3b, v19
	v_exp_f32_e32 v19, v19
	s_nop 0
	v_cndmask_b32_e32 v19, 0, v19, vcc
	v_cmp_le_u32_e32 vcc, v20, v101
	v_or_b32_e32 v20, 50, v96
	s_nop 0
	v_cndmask_b32_e32 v18, 0, v21, vcc
	v_pk_mul_f32 v[8:9], v[8:9], v[18:19]
	v_or_b32_e32 v19, v20, v171
	v_add_f32_e32 v17, v17, v8
	v_cvt_pk_bf16_f32 v72, v8, v9
	v_lshlrev_b32_e32 v8, 2, v92
	v_lshlrev_b32_e32 v19, 2, v19
	ds_bpermute_b32 v19, v19, v183
	v_or_b32_e32 v18, 51, v49
	v_cmp_le_u32_e32 vcc, v18, v101
	v_add_f32_e32 v17, v17, v9
	v_lshlrev_b32_e32 v92, 1, v92
	s_waitcnt lgkmcnt(0)
	v_add_f32_e32 v19, v50, v19
	v_mul_f32_e32 v19, 0x3fb8aa3b, v19
	v_exp_f32_e32 v21, v19
	v_or_b32_e32 v19, v18, v171
	v_lshlrev_b32_e32 v19, 2, v19
	ds_bpermute_b32 v19, v19, v183
	s_waitcnt lgkmcnt(0)
	v_add_f32_e32 v19, v50, v19
	v_mul_f32_e32 v19, 0x3fb8aa3b, v19
	v_exp_f32_e32 v19, v19
	s_nop 0
	v_cndmask_b32_e32 v19, 0, v19, vcc
	v_cmp_le_u32_e32 vcc, v20, v101
	v_or_b32_e32 v20, 56, v96
	s_nop 0
	v_cndmask_b32_e32 v18, 0, v21, vcc
	v_pk_mul_f32 v[10:11], v[10:11], v[18:19]
	v_or_b32_e32 v19, v20, v171
	v_lshlrev_b32_e32 v19, 2, v19
	ds_bpermute_b32 v19, v19, v183
	v_or_b32_e32 v18, 57, v49
	v_cmp_le_u32_e32 vcc, v18, v101
	v_add_f32_e32 v17, v17, v10
	v_add_f32_e32 v17, v17, v11
	s_waitcnt lgkmcnt(0)
	v_add_f32_e32 v19, v50, v19
	v_mul_f32_e32 v19, 0x3fb8aa3b, v19
	v_exp_f32_e32 v21, v19
	v_or_b32_e32 v19, v18, v171
	v_lshlrev_b32_e32 v19, 2, v19
	ds_bpermute_b32 v19, v19, v183
	v_cvt_pk_bf16_f32 v73, v10, v11
	v_and_b32_e32 v11, 0xffff0000, v44
	v_lshlrev_b32_e32 v10, 16, v44
	s_waitcnt lgkmcnt(0)
	v_add_f32_e32 v19, v50, v19
	v_mul_f32_e32 v19, 0x3fb8aa3b, v19
	v_exp_f32_e32 v19, v19
	s_waitcnt vmcnt(6)
	v_mul_f32_e32 v9, v109, v11
	v_cndmask_b32_e32 v19, 0, v19, vcc
	v_cmp_le_u32_e32 vcc, v20, v101
	v_or_b32_e32 v20, 58, v96
	v_fmac_f32_e32 v9, v108, v10
	v_cndmask_b32_e32 v18, 0, v21, vcc
	v_pk_mul_f32 v[12:13], v[12:13], v[18:19]
	v_or_b32_e32 v19, v20, v171
	v_lshlrev_b32_e32 v19, 2, v19
	ds_bpermute_b32 v19, v19, v183
	v_or_b32_e32 v18, 59, v49
	v_pk_mul_f32 v[4:5], v[98:99], v[10:11] op_sel_hi:[0,1]
	v_cvt_pk_bf16_f32 v48, v4, v5
	v_lshlrev_b32_e32 v4, 16, v45
	s_waitcnt lgkmcnt(0)
	v_add_f32_e32 v19, v50, v19
	v_mul_f32_e32 v19, 0x3fb8aa3b, v19
	v_exp_f32_e32 v21, v19
	v_or_b32_e32 v19, v18, v171
	v_lshlrev_b32_e32 v19, 2, v19
	ds_bpermute_b32 v19, v19, v183
	v_and_b32_e32 v5, 0xffff0000, v45
	v_fmac_f32_e32 v9, v110, v4
	v_fmac_f32_e32 v9, v111, v5
	v_pk_mul_f32 v[4:5], v[98:99], v[4:5] op_sel_hi:[0,1]
	v_cvt_pk_bf16_f32 v49, v4, v5
	v_lshlrev_b32_e32 v4, 16, v46
	v_and_b32_e32 v5, 0xffff0000, v46
	v_fmac_f32_e32 v9, v112, v4
	v_fmac_f32_e32 v9, v113, v5
	v_pk_mul_f32 v[0:1], v[98:99], v[4:5] op_sel_hi:[0,1]
	s_waitcnt lgkmcnt(0)
	v_add_f32_e32 v19, v50, v19
	v_cvt_pk_bf16_f32 v50, v0, v1
	v_lshlrev_b32_e32 v0, 16, v47
	v_and_b32_e32 v1, 0xffff0000, v47
	v_fmac_f32_e32 v9, v114, v0
	v_fmac_f32_e32 v9, v115, v1
	v_pk_mul_f32 v[0:1], v[98:99], v[0:1] op_sel_hi:[0,1]
	v_cvt_pk_bf16_f32 v51, v0, v1
	v_and_b32_e32 v11, 0xffff0000, v40
	v_add_f32_e32 v17, v17, v12
	v_cvt_pk_bf16_f32 v74, v12, v13
	v_lshlrev_b32_e32 v10, 16, v40
	v_add_f32_e32 v9, 0, v9
	v_mul_f32_e32 v19, 0x3fb8aa3b, v19
	v_exp_f32_e32 v19, v19
	v_cmp_le_u32_e32 vcc, v18, v101
	v_add_f32_e32 v17, v17, v13
	s_waitcnt vmcnt(4)
	v_mul_f32_e32 v12, v117, v11
	v_fmac_f32_e32 v12, v116, v10
	v_pk_mul_f32 v[4:5], v[98:99], v[10:11] op_sel_hi:[0,1]
	v_cvt_pk_bf16_f32 v80, v4, v5
	v_lshlrev_b32_e32 v4, 16, v41
	v_and_b32_e32 v5, 0xffff0000, v41
	v_fmac_f32_e32 v12, v118, v4
	v_fmac_f32_e32 v12, v119, v5
	v_pk_mul_f32 v[4:5], v[98:99], v[4:5] op_sel_hi:[0,1]
	v_cvt_pk_bf16_f32 v81, v4, v5
	v_lshlrev_b32_e32 v4, 16, v42
	v_and_b32_e32 v5, 0xffff0000, v42
	v_fmac_f32_e32 v12, v120, v4
	v_fmac_f32_e32 v12, v121, v5
	v_pk_mul_f32 v[0:1], v[98:99], v[4:5] op_sel_hi:[0,1]
	v_cvt_pk_bf16_f32 v82, v0, v1
	v_lshlrev_b32_e32 v0, 16, v43
	v_and_b32_e32 v1, 0xffff0000, v43
	v_fmac_f32_e32 v12, v122, v0
	v_fmac_f32_e32 v12, v123, v1
	v_pk_mul_f32 v[0:1], v[98:99], v[0:1] op_sel_hi:[0,1]
	v_cvt_pk_bf16_f32 v83, v0, v1
	v_and_b32_e32 v11, 0xffff0000, v36
	v_add_f32_e32 v9, v9, v12
	v_lshlrev_b32_e32 v10, 16, v36
	v_cndmask_b32_e32 v19, 0, v19, vcc
	v_cmp_le_u32_e32 vcc, v20, v101
	s_waitcnt vmcnt(2)
	v_mul_f32_e32 v12, v125, v11
	v_fmac_f32_e32 v12, v124, v10
	v_pk_mul_f32 v[4:5], v[98:99], v[10:11] op_sel_hi:[0,1]
	v_cvt_pk_bf16_f32 v84, v4, v5
	v_lshlrev_b32_e32 v4, 16, v37
	v_and_b32_e32 v5, 0xffff0000, v37
	v_fmac_f32_e32 v12, v126, v4
	v_fmac_f32_e32 v12, v127, v5
	v_pk_mul_f32 v[4:5], v[98:99], v[4:5] op_sel_hi:[0,1]
	v_cvt_pk_bf16_f32 v85, v4, v5
	v_lshlrev_b32_e32 v4, 16, v38
	v_and_b32_e32 v5, 0xffff0000, v38
	v_fmac_f32_e32 v12, v128, v4
	v_fmac_f32_e32 v12, v129, v5
	v_pk_mul_f32 v[0:1], v[98:99], v[4:5] op_sel_hi:[0,1]
	v_cvt_pk_bf16_f32 v86, v0, v1
	v_lshlrev_b32_e32 v0, 16, v39
	v_and_b32_e32 v1, 0xffff0000, v39
	v_fmac_f32_e32 v12, v130, v0
	v_fmac_f32_e32 v12, v131, v1
	v_pk_mul_f32 v[0:1], v[98:99], v[0:1] op_sel_hi:[0,1]
	v_cvt_pk_bf16_f32 v87, v0, v1
	v_add_f32_e32 v10, v9, v12
	v_and_b32_e32 v9, 0xffff0000, v32
	v_lshlrev_b32_e32 v8, 16, v32
	v_cndmask_b32_e32 v18, 0, v21, vcc
	v_pk_mul_f32 v[14:15], v[14:15], v[18:19]
	s_andn2_b64 vcc, exec, s[24:25]
	v_add_f32_e32 v17, v17, v14
	v_add_f32_e32 v187, v17, v15
	v_cvt_pk_bf16_f32 v75, v14, v15
	v_mul_u32_u24_e32 v17, 0x2400, v181
	ds_bpermute_b32 v188, v186, v187
	s_waitcnt vmcnt(0)
	v_mul_f32_e32 v11, v133, v9
	v_fmac_f32_e32 v11, v132, v8
	v_pk_mul_f32 v[4:5], v[98:99], v[8:9] op_sel_hi:[0,1]
	v_cvt_pk_bf16_f32 v88, v4, v5
	v_lshlrev_b32_e32 v4, 16, v33
	v_and_b32_e32 v5, 0xffff0000, v33
	v_fmac_f32_e32 v11, v134, v4
	v_fmac_f32_e32 v11, v135, v5
	v_pk_mul_f32 v[4:5], v[98:99], v[4:5] op_sel_hi:[0,1]
	v_cvt_pk_bf16_f32 v89, v4, v5
	v_lshlrev_b32_e32 v4, 16, v34
	v_and_b32_e32 v5, 0xffff0000, v34
	v_fmac_f32_e32 v11, v136, v4
	v_fmac_f32_e32 v11, v137, v5
	v_pk_mul_f32 v[0:1], v[98:99], v[4:5] op_sel_hi:[0,1]
	v_cvt_pk_bf16_f32 v90, v0, v1
	v_lshlrev_b32_e32 v0, 16, v35
	v_and_b32_e32 v1, 0xffff0000, v35
	v_fmac_f32_e32 v11, v138, v0
	v_fmac_f32_e32 v11, v139, v1
	v_pk_mul_f32 v[0:1], v[98:99], v[0:1] op_sel_hi:[0,1]
	v_cvt_pk_bf16_f32 v91, v0, v1
	v_lshl_add_u64 v[0:1], s[8:9], 0, v[92:93]
	v_lshlrev_b32_e32 v92, 1, v102
	v_lshl_add_u64 v[106:107], v[0:1], 0, v[92:93]
	v_add_f32_e32 v189, v10, v11
	v_lshlrev_b32_e32 v92, 1, v17
	v_lshl_add_u64 v[108:109], v[94:95], 0, v[92:93]
	ds_bpermute_b32 v190, v186, v189
	v_lshl_add_u64 v[102:103], v[108:109], 0, s[12:13]
	v_mul_u32_u24_e32 v18, 0x900, v104
	v_lshlrev_b32_e32 v92, 1, v18
	v_mul_u32_u24_e32 v19, 0x900, v100
	v_lshl_add_u64 v[114:115], v[94:95], 0, v[92:93]
	v_lshlrev_b32_e32 v92, 1, v19
	v_mul_u32_u24_e32 v20, 0x900, v97
	v_lshl_add_u64 v[110:111], v[94:95], 0, v[92:93]
	v_lshlrev_b32_e32 v92, 1, v20
	v_mul_u32_u24_e32 v20, 0x900, v62
	v_lshl_add_u64 v[112:113], v[94:95], 0, v[92:93]
	v_lshlrev_b32_e32 v92, 1, v20
	v_mul_u32_u24_e32 v21, 0x900, v63
	v_lshl_add_u64 v[116:117], v[94:95], 0, v[92:93]
	v_lshlrev_b32_e32 v92, 1, v21
	v_mul_u32_u24_e32 v21, 0x900, v60
	v_lshl_add_u64 v[120:121], v[94:95], 0, v[92:93]
	v_lshlrev_b32_e32 v92, 1, v21
	v_lshl_add_u64 v[118:119], v[94:95], 0, v[92:93]
	v_lshlrev_b32_e32 v92, 1, v24
	v_lshl_add_u64 v[122:123], v[94:95], 0, v[92:93]
	v_mul_u32_u24_e32 v17, 0x900, v58
	v_lshlrev_b32_e32 v92, 1, v17
	v_lshl_add_u64 v[134:135], v[94:95], 0, v[92:93]
	v_mul_u32_u24_e32 v24, 0x900, v53
	v_mul_u32_u24_e32 v18, 0x900, v59
	v_lshlrev_b32_e32 v92, 1, v18
	v_mul_u32_u24_e32 v19, 0x900, v56
	v_lshl_add_u64 v[138:139], v[94:95], 0, v[92:93]
	v_lshlrev_b32_e32 v92, 1, v19
	v_mul_u32_u24_e32 v20, 0x900, v57
	v_lshl_add_u64 v[124:125], v[94:95], 0, v[92:93]
	v_lshlrev_b32_e32 v92, 1, v20
	v_mul_u32_u24_e32 v20, 0x900, v54
	v_lshl_add_u64 v[126:127], v[94:95], 0, v[92:93]
	v_lshlrev_b32_e32 v92, 1, v20
	v_mul_u32_u24_e32 v21, 0x900, v55
	v_lshl_add_u64 v[128:129], v[94:95], 0, v[92:93]
	v_lshlrev_b32_e32 v92, 1, v21
	v_mul_u32_u24_e32 v21, 0x900, v52
	v_lshl_add_u64 v[130:131], v[94:95], 0, v[92:93]
	v_lshlrev_b32_e32 v92, 1, v21
	v_lshl_add_u64 v[132:133], v[94:95], 0, v[92:93]
	v_lshlrev_b32_e32 v92, 1, v24
	v_lshl_add_u64 v[136:137], v[94:95], 0, v[92:93]
	v_cndmask_b32_e64 v17, 0, 1, s[24:25]
	v_cmp_ne_u32_e64 s[4:5], 1, v17
	s_andn2_b64 vcc, exec, s[24:25]
	s_cbranch_vccnz .Lp6_v1skip_0
	v_mov_b32_e32 v253, 0
	v_mov_b32_e32 v149, v93
	v_lshl_add_u64 v[250:251], v[94:95], 0, v[148:149]
	global_load_ushort v228, v[250:251], off offset:2368
	v_mov_b32_e32 v252, 0x25000
	v_lshl_add_u64 v[250:251], v[102:103], 0, v[252:253]
	global_load_ushort v229, v[250:251], off offset:512
	v_mov_b32_e32 v252, 0x26000
	v_lshl_add_u64 v[250:251], v[102:103], 0, v[252:253]
	global_load_ushort v230, v[250:251], off offset:1024
	v_mov_b32_e32 v252, 0x27000
	v_lshl_add_u64 v[250:251], v[102:103], 0, v[252:253]
	global_load_ushort v231, v[250:251], off offset:1536
	v_mov_b32_e32 v252, 0x2d000
	v_lshl_add_u64 v[250:251], v[102:103], 0, v[252:253]
	global_load_ushort v232, v[250:251], off
	v_mov_b32_e32 v252, 0x2e000
	v_lshl_add_u64 v[250:251], v[102:103], 0, v[252:253]
	global_load_ushort v233, v[250:251], off offset:512
	v_mov_b32_e32 v252, 0x2f000
	v_lshl_add_u64 v[250:251], v[102:103], 0, v[252:253]
	global_load_ushort v234, v[250:251], off offset:1024
	v_mov_b32_e32 v252, 0x30000
	v_lshl_add_u64 v[250:251], v[102:103], 0, v[252:253]
	global_load_ushort v235, v[250:251], off offset:1536
	v_mov_b32_e32 v252, 0x36000
	v_lshl_add_u64 v[250:251], v[102:103], 0, v[252:253]
	global_load_ushort v236, v[250:251], off
	v_mov_b32_e32 v252, 0x37000
	v_lshl_add_u64 v[250:251], v[102:103], 0, v[252:253]
	global_load_ushort v237, v[250:251], off offset:512
	v_mov_b32_e32 v252, 0x38000
	v_lshl_add_u64 v[250:251], v[102:103], 0, v[252:253]
	global_load_ushort v238, v[250:251], off offset:1024
	v_mov_b32_e32 v252, 0x39000
	v_lshl_add_u64 v[250:251], v[102:103], 0, v[252:253]
	global_load_ushort v239, v[250:251], off offset:1536
	v_mov_b32_e32 v252, 0x3f000
	v_lshl_add_u64 v[250:251], v[102:103], 0, v[252:253]
	global_load_ushort v240, v[250:251], off
	v_mov_b32_e32 v252, 0x40000
	v_lshl_add_u64 v[250:251], v[102:103], 0, v[252:253]
	global_load_ushort v241, v[250:251], off offset:512
	v_mov_b32_e32 v252, 0x41000
	v_lshl_add_u64 v[250:251], v[102:103], 0, v[252:253]
	global_load_ushort v242, v[250:251], off offset:1024
	v_mov_b32_e32 v252, 0x42000
	v_lshl_add_u64 v[250:251], v[102:103], 0, v[252:253]
	global_load_ushort v243, v[250:251], off offset:1536
.Lp6_v1skip_0:
	global_load_dwordx4 v[196:199], v[106:107], off
	global_load_dwordx4 v[200:203], v[106:107], off offset:32
	global_load_dwordx4 v[204:207], v[106:107], off offset:64
	global_load_dwordx4 v[208:211], v[106:107], off offset:96
	global_load_ushort v212, v[108:109], off offset:2368
	global_load_ushort v213, v[114:115], off offset:2368
	global_load_ushort v214, v[110:111], off offset:2368
	global_load_ushort v215, v[112:113], off offset:2368
	global_load_ushort v216, v[116:117], off offset:2368
	global_load_ushort v217, v[120:121], off offset:2368
	global_load_ushort v218, v[118:119], off offset:2368
	global_load_ushort v219, v[122:123], off offset:2368
	global_load_ushort v220, v[134:135], off offset:2368
	global_load_ushort v221, v[138:139], off offset:2368
	global_load_ushort v222, v[124:125], off offset:2368
	global_load_ushort v223, v[126:127], off offset:2368
	global_load_ushort v224, v[128:129], off offset:2368
	global_load_ushort v225, v[130:131], off offset:2368
	global_load_ushort v226, v[132:133], off offset:2368
	global_load_ushort v227, v[136:137], off offset:2368
	s_waitcnt vmcnt(19)
	v_mfma_f32_32x32x16_bf16 v[0:15], v[196:199], v[48:51], 0
	s_waitcnt vmcnt(18)
	v_mfma_f32_32x32x16_bf16 v[0:15], v[200:203], v[80:83], v[0:15]
	s_waitcnt vmcnt(17)
	v_mfma_f32_32x32x16_bf16 v[0:15], v[204:207], v[84:87], v[0:15]
	s_waitcnt vmcnt(16)
	v_mfma_f32_32x32x16_bf16 v[0:15], v[208:211], v[88:91], v[0:15]
	s_waitcnt vmcnt(8)
	v_perm_b32 v212, v213, v212, s37
	v_perm_b32 v213, v215, v214, s37
	v_perm_b32 v214, v217, v216, s37
	v_perm_b32 v215, v219, v218, s37
	s_nop 1
	v_mfma_f32_32x32x16_bf16 v[0:15], v[212:215], v[68:71], v[0:15]
	s_waitcnt vmcnt(0)
	v_perm_b32 v220, v221, v220, s37
	v_perm_b32 v221, v223, v222, s37
	v_perm_b32 v222, v225, v224, s37
	v_perm_b32 v223, v227, v226, s37
	s_nop 1
	v_mfma_f32_32x32x16_bf16 v[0:15], v[220:223], v[64:67], v[0:15]
	s_cbranch_vccnz .LBB0_857
	v_perm_b32 v228, v229, v228, s37
	v_perm_b32 v229, v231, v230, s37
	v_perm_b32 v230, v233, v232, s37
	v_perm_b32 v231, v235, v234, s37
	v_perm_b32 v236, v237, v236, s37
	v_perm_b32 v237, v239, v238, s37
	v_perm_b32 v238, v241, v240, s37
	v_perm_b32 v239, v243, v242, s37
	s_nop 1
	v_mfma_f32_32x32x16_bf16 v[0:15], v[228:231], v[76:79], v[0:15]
	v_mfma_f32_32x32x16_bf16 v[0:15], v[236:239], v[72:75], v[0:15]
.LBB0_857:
	v_or_b32_e32 v100, s16, v101
	v_mov_b64_e32 v[16:17], s[20:21]
	s_mul_i32 s2, s17, 0x1200
	v_mad_u64_u32 v[16:17], s[24:25], v100, s35, v[16:17]
	v_add_u32_e32 v17, s2, v17
	v_lshlrev_b32_e32 v92, 1, v96
	v_lshl_add_u64 v[104:105], v[16:17], 0, v[92:93]
	v_add_co_u32_e32 v36, vcc, s36, v106
	global_load_dwordx2 v[146:147], v[104:105], off offset:3392
	global_load_dwordx2 v[144:145], v[104:105], off offset:3408
	global_load_dwordx2 v[142:143], v[104:105], off offset:3424
	global_load_dwordx2 v[140:141], v[104:105], off offset:3440
	v_addc_co_u32_e32 v37, vcc, 0, v107, vcc
	v_mov_b32_e32 v101, s17
	s_and_b64 vcc, exec, s[4:5]
	s_cbranch_vccnz .Lp6_v1skip_1
	v_mov_b32_e32 v253, 0
	v_mov_b32_e32 v149, v93
	v_lshl_add_u64 v[250:251], v[94:95], 0, v[148:149]
	global_load_ushort v228, v[250:251], off offset:2432
	v_mov_b32_e32 v252, 0x25000
	v_lshl_add_u64 v[250:251], v[102:103], 0, v[252:253]
	global_load_ushort v229, v[250:251], off offset:576
	v_mov_b32_e32 v252, 0x26000
	v_lshl_add_u64 v[250:251], v[102:103], 0, v[252:253]
	global_load_ushort v230, v[250:251], off offset:1088
	v_mov_b32_e32 v252, 0x27000
	v_lshl_add_u64 v[250:251], v[102:103], 0, v[252:253]
	global_load_ushort v231, v[250:251], off offset:1600
	v_mov_b32_e32 v252, 0x2d000
	v_lshl_add_u64 v[250:251], v[102:103], 0, v[252:253]
	global_load_ushort v232, v[250:251], off offset:64
	v_mov_b32_e32 v252, 0x2e000
	v_lshl_add_u64 v[250:251], v[102:103], 0, v[252:253]
	global_load_ushort v233, v[250:251], off offset:576
	v_mov_b32_e32 v252, 0x2f000
	v_lshl_add_u64 v[250:251], v[102:103], 0, v[252:253]
	global_load_ushort v234, v[250:251], off offset:1088
	v_mov_b32_e32 v252, 0x30000
	v_lshl_add_u64 v[250:251], v[102:103], 0, v[252:253]
	global_load_ushort v235, v[250:251], off offset:1600
	v_mov_b32_e32 v252, 0x36000
	v_lshl_add_u64 v[250:251], v[102:103], 0, v[252:253]
	global_load_ushort v236, v[250:251], off offset:64
	v_mov_b32_e32 v252, 0x37000
	v_lshl_add_u64 v[250:251], v[102:103], 0, v[252:253]
	global_load_ushort v237, v[250:251], off offset:576
	v_mov_b32_e32 v252, 0x38000
	v_lshl_add_u64 v[250:251], v[102:103], 0, v[252:253]
	global_load_ushort v238, v[250:251], off offset:1088
	v_mov_b32_e32 v252, 0x39000
	v_lshl_add_u64 v[250:251], v[102:103], 0, v[252:253]
	global_load_ushort v239, v[250:251], off offset:1600
	v_mov_b32_e32 v252, 0x3f000
	v_lshl_add_u64 v[250:251], v[102:103], 0, v[252:253]
	global_load_ushort v240, v[250:251], off offset:64
	v_mov_b32_e32 v252, 0x40000
	v_lshl_add_u64 v[250:251], v[102:103], 0, v[252:253]
	global_load_ushort v241, v[250:251], off offset:576
	v_mov_b32_e32 v252, 0x41000
	v_lshl_add_u64 v[250:251], v[102:103], 0, v[252:253]
	global_load_ushort v242, v[250:251], off offset:1088
	v_mov_b32_e32 v252, 0x42000
	v_lshl_add_u64 v[250:251], v[102:103], 0, v[252:253]
	global_load_ushort v243, v[250:251], off offset:1600
.Lp6_v1skip_1:
	global_load_dwordx4 v[196:199], v[36:37], off
	global_load_dwordx4 v[200:203], v[36:37], off offset:32
	global_load_dwordx4 v[204:207], v[36:37], off offset:64
	global_load_dwordx4 v[208:211], v[36:37], off offset:96
	global_load_ushort v212, v[108:109], off offset:2432
	global_load_ushort v213, v[114:115], off offset:2432
	global_load_ushort v214, v[110:111], off offset:2432
	global_load_ushort v215, v[112:113], off offset:2432
	global_load_ushort v216, v[116:117], off offset:2432
	global_load_ushort v217, v[120:121], off offset:2432
	global_load_ushort v218, v[118:119], off offset:2432
	global_load_ushort v219, v[122:123], off offset:2432
	global_load_ushort v220, v[134:135], off offset:2432
	global_load_ushort v221, v[138:139], off offset:2432
	global_load_ushort v222, v[124:125], off offset:2432
	global_load_ushort v223, v[126:127], off offset:2432
	global_load_ushort v224, v[128:129], off offset:2432
	global_load_ushort v225, v[130:131], off offset:2432
	global_load_ushort v226, v[132:133], off offset:2432
	global_load_ushort v227, v[136:137], off offset:2432
	s_waitcnt vmcnt(19)
	v_mfma_f32_32x32x16_bf16 v[16:31], v[196:199], v[48:51], 0
	s_waitcnt vmcnt(18)
	v_mfma_f32_32x32x16_bf16 v[16:31], v[200:203], v[80:83], v[16:31]
	s_waitcnt vmcnt(17)
	v_mfma_f32_32x32x16_bf16 v[16:31], v[204:207], v[84:87], v[16:31]
	s_waitcnt vmcnt(16)
	v_mfma_f32_32x32x16_bf16 v[16:31], v[208:211], v[88:91], v[16:31]
	s_waitcnt vmcnt(8)
	v_perm_b32 v212, v213, v212, s37
	v_perm_b32 v213, v215, v214, s37
	v_perm_b32 v214, v217, v216, s37
	v_perm_b32 v215, v219, v218, s37
	s_nop 1
	v_mfma_f32_32x32x16_bf16 v[16:31], v[212:215], v[68:71], v[16:31]
	s_waitcnt vmcnt(0)
	v_perm_b32 v220, v221, v220, s37
	v_perm_b32 v221, v223, v222, s37
	v_perm_b32 v222, v225, v224, s37
	v_perm_b32 v223, v227, v226, s37
	s_nop 1
	v_mfma_f32_32x32x16_bf16 v[16:31], v[220:223], v[64:67], v[16:31]
	s_cbranch_vccnz .LBB0_859
	v_perm_b32 v228, v229, v228, s37
	v_perm_b32 v229, v231, v230, s37
	v_perm_b32 v230, v233, v232, s37
	v_perm_b32 v231, v235, v234, s37
	v_perm_b32 v236, v237, v236, s37
	v_perm_b32 v237, v239, v238, s37
	v_perm_b32 v238, v241, v240, s37
	v_perm_b32 v239, v243, v242, s37
	s_nop 1
	v_mfma_f32_32x32x16_bf16 v[16:31], v[228:231], v[76:79], v[16:31]
	v_mfma_f32_32x32x16_bf16 v[16:31], v[236:239], v[72:75], v[16:31]
.LBB0_859:
	v_add_co_u32_e32 v56, vcc, 0x2000, v106
	global_load_dwordx2 v[156:157], v[104:105], off offset:3456
	global_load_dwordx2 v[154:155], v[104:105], off offset:3472
	global_load_dwordx2 v[152:153], v[104:105], off offset:3488
	global_load_dwordx2 v[150:151], v[104:105], off offset:3504
	v_addc_co_u32_e32 v57, vcc, 0, v107, vcc
	s_and_b64 vcc, exec, s[4:5]
	s_cbranch_vccnz .Lp6_v1skip_2
	v_mov_b32_e32 v253, 0
	v_mov_b32_e32 v149, v93
	v_lshl_add_u64 v[250:251], v[94:95], 0, v[148:149]
	global_load_ushort v228, v[250:251], off offset:2496
	v_mov_b32_e32 v252, 0x25000
	v_lshl_add_u64 v[250:251], v[102:103], 0, v[252:253]
	global_load_ushort v229, v[250:251], off offset:640
	v_mov_b32_e32 v252, 0x26000
	v_lshl_add_u64 v[250:251], v[102:103], 0, v[252:253]
	global_load_ushort v230, v[250:251], off offset:1152
	v_mov_b32_e32 v252, 0x27000
	v_lshl_add_u64 v[250:251], v[102:103], 0, v[252:253]
	global_load_ushort v231, v[250:251], off offset:1664
	v_mov_b32_e32 v252, 0x2d000
	v_lshl_add_u64 v[250:251], v[102:103], 0, v[252:253]
	global_load_ushort v232, v[250:251], off offset:128
	v_mov_b32_e32 v252, 0x2e000
	v_lshl_add_u64 v[250:251], v[102:103], 0, v[252:253]
	global_load_ushort v233, v[250:251], off offset:640
	v_mov_b32_e32 v252, 0x2f000
	v_lshl_add_u64 v[250:251], v[102:103], 0, v[252:253]
	global_load_ushort v234, v[250:251], off offset:1152
	v_mov_b32_e32 v252, 0x30000
	v_lshl_add_u64 v[250:251], v[102:103], 0, v[252:253]
	global_load_ushort v235, v[250:251], off offset:1664
	v_mov_b32_e32 v252, 0x36000
	v_lshl_add_u64 v[250:251], v[102:103], 0, v[252:253]
	global_load_ushort v236, v[250:251], off offset:128
	v_mov_b32_e32 v252, 0x37000
	v_lshl_add_u64 v[250:251], v[102:103], 0, v[252:253]
	global_load_ushort v237, v[250:251], off offset:640
	v_mov_b32_e32 v252, 0x38000
	v_lshl_add_u64 v[250:251], v[102:103], 0, v[252:253]
	global_load_ushort v238, v[250:251], off offset:1152
	v_mov_b32_e32 v252, 0x39000
	v_lshl_add_u64 v[250:251], v[102:103], 0, v[252:253]
	global_load_ushort v239, v[250:251], off offset:1664
	v_mov_b32_e32 v252, 0x3f000
	v_lshl_add_u64 v[250:251], v[102:103], 0, v[252:253]
	global_load_ushort v240, v[250:251], off offset:128
	v_mov_b32_e32 v252, 0x40000
	v_lshl_add_u64 v[250:251], v[102:103], 0, v[252:253]
	global_load_ushort v241, v[250:251], off offset:640
	v_mov_b32_e32 v252, 0x41000
	v_lshl_add_u64 v[250:251], v[102:103], 0, v[252:253]
	global_load_ushort v242, v[250:251], off offset:1152
	v_mov_b32_e32 v252, 0x42000
	v_lshl_add_u64 v[250:251], v[102:103], 0, v[252:253]
	global_load_ushort v243, v[250:251], off offset:1664
.Lp6_v1skip_2:
	global_load_dwordx4 v[196:199], v[56:57], off
	global_load_dwordx4 v[200:203], v[56:57], off offset:32
	global_load_dwordx4 v[204:207], v[56:57], off offset:64
	global_load_dwordx4 v[208:211], v[56:57], off offset:96
	global_load_ushort v212, v[108:109], off offset:2496
	global_load_ushort v213, v[114:115], off offset:2496
	global_load_ushort v214, v[110:111], off offset:2496
	global_load_ushort v215, v[112:113], off offset:2496
	global_load_ushort v216, v[116:117], off offset:2496
	global_load_ushort v217, v[120:121], off offset:2496
	global_load_ushort v218, v[118:119], off offset:2496
	global_load_ushort v219, v[122:123], off offset:2496
	global_load_ushort v220, v[134:135], off offset:2496
	global_load_ushort v221, v[138:139], off offset:2496
	global_load_ushort v222, v[124:125], off offset:2496
	global_load_ushort v223, v[126:127], off offset:2496
	global_load_ushort v224, v[128:129], off offset:2496
	global_load_ushort v225, v[130:131], off offset:2496
	global_load_ushort v226, v[132:133], off offset:2496
	global_load_ushort v227, v[136:137], off offset:2496
	s_waitcnt vmcnt(19)
	v_mfma_f32_32x32x16_bf16 v[32:47], v[196:199], v[48:51], 0
	s_waitcnt vmcnt(18)
	v_mfma_f32_32x32x16_bf16 v[32:47], v[200:203], v[80:83], v[32:47]
	s_waitcnt vmcnt(17)
	v_mfma_f32_32x32x16_bf16 v[32:47], v[204:207], v[84:87], v[32:47]
	s_waitcnt vmcnt(16)
	v_mfma_f32_32x32x16_bf16 v[32:47], v[208:211], v[88:91], v[32:47]
	s_waitcnt vmcnt(8)
	v_perm_b32 v212, v213, v212, s37
	v_perm_b32 v213, v215, v214, s37
	v_perm_b32 v214, v217, v216, s37
	v_perm_b32 v215, v219, v218, s37
	s_nop 1
	v_mfma_f32_32x32x16_bf16 v[32:47], v[212:215], v[68:71], v[32:47]
	s_waitcnt vmcnt(0)
	v_perm_b32 v220, v221, v220, s37
	v_perm_b32 v221, v223, v222, s37
	v_perm_b32 v222, v225, v224, s37
	v_perm_b32 v223, v227, v226, s37
	s_nop 1
	v_mfma_f32_32x32x16_bf16 v[32:47], v[220:223], v[64:67], v[32:47]
	s_cbranch_vccnz .LBB0_861
	v_perm_b32 v228, v229, v228, s37
	v_perm_b32 v229, v231, v230, s37
	v_perm_b32 v230, v233, v232, s37
	v_perm_b32 v231, v235, v234, s37
	v_perm_b32 v236, v237, v236, s37
	v_perm_b32 v237, v239, v238, s37
	v_perm_b32 v238, v241, v240, s37
	v_perm_b32 v239, v243, v242, s37
	s_nop 1
	v_mfma_f32_32x32x16_bf16 v[32:47], v[228:231], v[76:79], v[32:47]
	v_mfma_f32_32x32x16_bf16 v[32:47], v[236:239], v[72:75], v[32:47]
.LBB0_861:
	v_add_co_u32_e32 v106, vcc, 0x3000, v106
	global_load_dwordx2 v[164:165], v[104:105], off offset:3520
	global_load_dwordx2 v[162:163], v[104:105], off offset:3536
	global_load_dwordx2 v[160:161], v[104:105], off offset:3552
	global_load_dwordx2 v[158:159], v[104:105], off offset:3568
	v_addc_co_u32_e32 v107, vcc, 0, v107, vcc
	s_and_b64 vcc, exec, s[4:5]
	s_cbranch_vccnz .Lp6_v1skip_3
	v_mov_b32_e32 v253, 0
	v_mov_b32_e32 v149, v93
	v_lshl_add_u64 v[250:251], v[94:95], 0, v[148:149]
	global_load_ushort v228, v[250:251], off offset:2560
	v_mov_b32_e32 v252, 0x25000
	v_lshl_add_u64 v[250:251], v[102:103], 0, v[252:253]
	global_load_ushort v229, v[250:251], off offset:704
	v_mov_b32_e32 v252, 0x26000
	v_lshl_add_u64 v[250:251], v[102:103], 0, v[252:253]
	global_load_ushort v230, v[250:251], off offset:1216
	v_mov_b32_e32 v252, 0x27000
	v_lshl_add_u64 v[250:251], v[102:103], 0, v[252:253]
	global_load_ushort v231, v[250:251], off offset:1728
	v_mov_b32_e32 v252, 0x2d000
	v_lshl_add_u64 v[250:251], v[102:103], 0, v[252:253]
	global_load_ushort v232, v[250:251], off offset:192
	v_mov_b32_e32 v252, 0x2e000
	v_lshl_add_u64 v[250:251], v[102:103], 0, v[252:253]
	global_load_ushort v233, v[250:251], off offset:704
	v_mov_b32_e32 v252, 0x2f000
	v_lshl_add_u64 v[250:251], v[102:103], 0, v[252:253]
	global_load_ushort v234, v[250:251], off offset:1216
	v_mov_b32_e32 v252, 0x30000
	v_lshl_add_u64 v[250:251], v[102:103], 0, v[252:253]
	global_load_ushort v235, v[250:251], off offset:1728
	v_mov_b32_e32 v252, 0x36000
	v_lshl_add_u64 v[250:251], v[102:103], 0, v[252:253]
	global_load_ushort v236, v[250:251], off offset:192
	v_mov_b32_e32 v252, 0x37000
	v_lshl_add_u64 v[250:251], v[102:103], 0, v[252:253]
	global_load_ushort v237, v[250:251], off offset:704
	v_mov_b32_e32 v252, 0x38000
	v_lshl_add_u64 v[250:251], v[102:103], 0, v[252:253]
	global_load_ushort v238, v[250:251], off offset:1216
	v_mov_b32_e32 v252, 0x39000
	v_lshl_add_u64 v[250:251], v[102:103], 0, v[252:253]
	global_load_ushort v239, v[250:251], off offset:1728
	v_mov_b32_e32 v252, 0x3f000
	v_lshl_add_u64 v[250:251], v[102:103], 0, v[252:253]
	global_load_ushort v240, v[250:251], off offset:192
	v_mov_b32_e32 v252, 0x40000
	v_lshl_add_u64 v[250:251], v[102:103], 0, v[252:253]
	global_load_ushort v241, v[250:251], off offset:704
	v_mov_b32_e32 v252, 0x41000
	v_lshl_add_u64 v[250:251], v[102:103], 0, v[252:253]
	global_load_ushort v242, v[250:251], off offset:1216
	v_mov_b32_e32 v252, 0x42000
	v_lshl_add_u64 v[250:251], v[102:103], 0, v[252:253]
	global_load_ushort v243, v[250:251], off offset:1728
.Lp6_v1skip_3:
	global_load_dwordx4 v[196:199], v[106:107], off
	global_load_dwordx4 v[200:203], v[106:107], off offset:32
	global_load_dwordx4 v[204:207], v[106:107], off offset:64
	global_load_dwordx4 v[208:211], v[106:107], off offset:96
	global_load_ushort v212, v[108:109], off offset:2560
	global_load_ushort v213, v[114:115], off offset:2560
	global_load_ushort v214, v[110:111], off offset:2560
	global_load_ushort v215, v[112:113], off offset:2560
	global_load_ushort v216, v[116:117], off offset:2560
	global_load_ushort v217, v[120:121], off offset:2560
	global_load_ushort v218, v[118:119], off offset:2560
	global_load_ushort v219, v[122:123], off offset:2560
	global_load_ushort v220, v[134:135], off offset:2560
	global_load_ushort v221, v[138:139], off offset:2560
	global_load_ushort v222, v[124:125], off offset:2560
	global_load_ushort v223, v[126:127], off offset:2560
	global_load_ushort v224, v[128:129], off offset:2560
	global_load_ushort v225, v[130:131], off offset:2560
	global_load_ushort v226, v[132:133], off offset:2560
	global_load_ushort v227, v[136:137], off offset:2560
	s_waitcnt vmcnt(19)
	v_mfma_f32_32x32x16_bf16 v[48:63], v[196:199], v[48:51], 0
	s_waitcnt vmcnt(18)
	v_mfma_f32_32x32x16_bf16 v[48:63], v[200:203], v[80:83], v[48:63]
	s_waitcnt vmcnt(17)
	v_mfma_f32_32x32x16_bf16 v[48:63], v[204:207], v[84:87], v[48:63]
	s_waitcnt vmcnt(16)
	v_mfma_f32_32x32x16_bf16 v[48:63], v[208:211], v[88:91], v[48:63]
	s_waitcnt vmcnt(8)
	v_perm_b32 v212, v213, v212, s37
	v_perm_b32 v213, v215, v214, s37
	v_perm_b32 v214, v217, v216, s37
	v_perm_b32 v215, v219, v218, s37
	s_nop 1
	v_mfma_f32_32x32x16_bf16 v[48:63], v[212:215], v[68:71], v[48:63]
	s_waitcnt vmcnt(0)
	v_perm_b32 v220, v221, v220, s37
	v_perm_b32 v221, v223, v222, s37
	v_perm_b32 v222, v225, v224, s37
	v_perm_b32 v223, v227, v226, s37
	s_nop 1
	v_mfma_f32_32x32x16_bf16 v[48:63], v[220:223], v[64:67], v[48:63]
	s_cbranch_vccnz .LBB0_852
	v_perm_b32 v228, v229, v228, s37
	v_perm_b32 v229, v231, v230, s37
	v_perm_b32 v230, v233, v232, s37
	v_perm_b32 v231, v235, v234, s37
	v_perm_b32 v236, v237, v236, s37
	v_perm_b32 v237, v239, v238, s37
	v_perm_b32 v238, v241, v240, s37
	v_perm_b32 v239, v243, v242, s37
	s_nop 1
	v_mfma_f32_32x32x16_bf16 v[48:63], v[228:231], v[76:79], v[48:63]
	v_mfma_f32_32x32x16_bf16 v[48:63], v[236:239], v[72:75], v[48:63]
	s_branch .LBB0_852
